# MLP-up: the 32 last-round tiles split along K over workgroup pairs (K-tiles 0-15 / 16-31); f32 partial tile handed over with write-through stores + counter flag, consumer adds and runs the normal epil
# speedup vs baseline: 1.0086x; 1.0086x over previous
.LBB0_705:
	s_add_i32 s62, s62, 1
	s_mul_i32 s38, s62, s31
	s_mul_hi_u32 s39, s62, s82
	s_add_i32 s39, s39, s38
	s_mul_i32 s38, s62, s82
	s_add_u32 s46, s38, s2
	s_addc_u32 s47, s39, s3
	v_cmp_gt_i64_e32 vcc, s[46:47], v[178:179]
	v_cmp_lt_i64_e64 s[38:39], s[46:47], v[176:177]
	s_cbranch_vccnz .LBB0_707
	s_mov_b32 s99, 0
	s_cmpk_lt_i32 s46, 0x400
	s_cbranch_scc1 .Lmy_ht_full
	s_sub_i32 s99, s46, 0x400
	s_lshr_b32 s46, s99, 1
	s_add_i32 s46, s46, 0x400
	s_and_b32 s99, s99, 1
	s_add_i32 s99, s99, 1

.LBB0_707:
	s_ashr_i32 s45, s44, 31
	s_lshl_b64 s[46:47], s[44:45], 20
	s_add_u32 s46, s80, s46
	s_addc_u32 s47, s81, s47
	s_cmp_eq_u32 s99, 2
	s_cselect_b32 s100, 0x800, 0
	s_add_u32 s46, s46, s100
	s_addc_u32 s47, s47, 0
	s_and_b64 s[48:49], s[38:39], exec
	s_cselect_b32 s41, s47, s87
	s_cselect_b32 s45, s46, s86
	s_ashr_i32 s43, s42, 31
	s_lshl_b64 s[48:49], s[42:43], 20
	s_add_u32 s48, s56, s48
	s_addc_u32 s49, s55, s49
	s_add_u32 s48, s48, s100
	s_addc_u32 s49, s49, 0
	s_and_b64 s[64:65], s[38:39], exec
	s_cselect_b32 s43, s49, s9
	s_cselect_b32 s63, s48, s8
	s_add_u32 s86, s86, 0x80080
	s_addc_u32 s87, s87, 0
	s_add_u32 s64, s8, 0x100
	v_mov_b32_e32 v2, 0
	s_addc_u32 s65, s9, 0
	s_cmp_eq_u32 s98, 0
	s_cselect_b32 s66, -2, 14
	v_mov_b32_e32 v3, v2
	v_mov_b32_e32 v4, v2
	v_mov_b32_e32 v5, v2
	v_mov_b32_e32 v6, v2
	v_mov_b32_e32 v7, v2
	v_mov_b32_e32 v8, v2
	v_mov_b32_e32 v9, v2
	v_mov_b32_e32 v18, v2
	v_mov_b32_e32 v19, v2
	v_mov_b32_e32 v20, v2
	v_mov_b32_e32 v21, v2
	v_mov_b32_e32 v22, v2
	v_mov_b32_e32 v23, v2
	v_mov_b32_e32 v24, v2
	v_mov_b32_e32 v25, v2
	v_mov_b32_e32 v34, v2
	v_mov_b32_e32 v35, v2
	v_mov_b32_e32 v36, v2
	v_mov_b32_e32 v37, v2
	v_mov_b32_e32 v38, v2
	v_mov_b32_e32 v39, v2
	v_mov_b32_e32 v40, v2
	v_mov_b32_e32 v41, v2
	v_mov_b32_e32 v50, v2
	v_mov_b32_e32 v51, v2
	v_mov_b32_e32 v52, v2
	v_mov_b32_e32 v53, v2
	v_mov_b32_e32 v54, v2
	v_mov_b32_e32 v55, v2
	v_mov_b32_e32 v56, v2
	v_mov_b32_e32 v57, v2
	v_mov_b32_e32 v10, v2
	v_mov_b32_e32 v11, v2
	v_mov_b32_e32 v12, v2
	v_mov_b32_e32 v13, v2
	v_mov_b32_e32 v14, v2
	v_mov_b32_e32 v15, v2
	v_mov_b32_e32 v16, v2
	v_mov_b32_e32 v17, v2
	v_mov_b32_e32 v26, v2
	v_mov_b32_e32 v27, v2
	v_mov_b32_e32 v28, v2
	v_mov_b32_e32 v29, v2
	v_mov_b32_e32 v30, v2
	v_mov_b32_e32 v31, v2
	v_mov_b32_e32 v32, v2
	v_mov_b32_e32 v33, v2
	v_mov_b32_e32 v42, v2
	v_mov_b32_e32 v43, v2
	v_mov_b32_e32 v44, v2
	v_mov_b32_e32 v45, v2
	v_mov_b32_e32 v46, v2
	v_mov_b32_e32 v47, v2
	v_mov_b32_e32 v48, v2
	v_mov_b32_e32 v49, v2
	v_mov_b32_e32 v58, v2
	v_mov_b32_e32 v59, v2
	v_mov_b32_e32 v60, v2
	v_mov_b32_e32 v61, v2
	v_mov_b32_e32 v62, v2
	v_mov_b32_e32 v63, v2
	v_mov_b32_e32 v64, v2
	v_mov_b32_e32 v65, v2
	v_mov_b32_e32 v66, v2
	v_mov_b32_e32 v67, v2
	v_mov_b32_e32 v68, v2
	v_mov_b32_e32 v69, v2
	v_mov_b32_e32 v70, v2
	v_mov_b32_e32 v71, v2
	v_mov_b32_e32 v72, v2
	v_mov_b32_e32 v73, v2
	v_mov_b32_e32 v82, v2
	v_mov_b32_e32 v83, v2
	v_mov_b32_e32 v84, v2
	v_mov_b32_e32 v85, v2
	v_mov_b32_e32 v86, v2
	v_mov_b32_e32 v87, v2
	v_mov_b32_e32 v88, v2
	v_mov_b32_e32 v89, v2
	v_mov_b32_e32 v98, v2
	v_mov_b32_e32 v99, v2
	v_mov_b32_e32 v100, v2
	v_mov_b32_e32 v101, v2
	v_mov_b32_e32 v102, v2
	v_mov_b32_e32 v103, v2
	v_mov_b32_e32 v104, v2
	v_mov_b32_e32 v105, v2
	v_mov_b32_e32 v120, v2
	v_mov_b32_e32 v121, v2
	v_mov_b32_e32 v122, v2
	v_mov_b32_e32 v123, v2
	v_mov_b32_e32 v124, v2
	v_mov_b32_e32 v125, v2
	v_mov_b32_e32 v126, v2
	v_mov_b32_e32 v127, v2
	v_mov_b32_e32 v74, v2
	v_mov_b32_e32 v75, v2
	v_mov_b32_e32 v76, v2
	v_mov_b32_e32 v77, v2
	v_mov_b32_e32 v78, v2
	v_mov_b32_e32 v79, v2
	v_mov_b32_e32 v80, v2
	v_mov_b32_e32 v81, v2
	v_mov_b32_e32 v90, v2
	v_mov_b32_e32 v91, v2
	v_mov_b32_e32 v92, v2
	v_mov_b32_e32 v93, v2
	v_mov_b32_e32 v94, v2
	v_mov_b32_e32 v95, v2
	v_mov_b32_e32 v96, v2
	v_mov_b32_e32 v97, v2
	v_mov_b32_e32 v106, v2
	v_mov_b32_e32 v107, v2
	v_mov_b32_e32 v108, v2
	v_mov_b32_e32 v109, v2
	v_mov_b32_e32 v116, v2
	v_mov_b32_e32 v117, v2
	v_mov_b32_e32 v118, v2
	v_mov_b32_e32 v119, v2
	v_mov_b32_e32 v128, v2
	v_mov_b32_e32 v129, v2
	v_mov_b32_e32 v130, v2
	v_mov_b32_e32 v131, v2
	v_mov_b32_e32 v132, v2
	v_mov_b32_e32 v133, v2
	v_mov_b32_e32 v134, v2
	v_mov_b32_e32 v135, v2

.LBB0_711:
	s_cmp_eq_u32 s98, 0
	s_cbranch_scc1 .Lmy_sk_norm
	s_cmp_eq_u32 s98, 2
	s_cbranch_scc1 .Lmy_sk_prod
	s_branch .Lmy_sk_cons
.Lmy_sk_prod:
	s_lshr_b32 s100, s2, 1
	s_lshl_b32 s100, s100, 18
	s_add_u32 s100, s76, s100
	s_addc_u32 s101, s77, 0
	s_add_u32 s100, s100, 0x1a900000
	s_addc_u32 s101, s101, 0
	v_readfirstlane_b32 s99, v164
	s_lshr_b32 s99, s99, 6
	s_lshl_b32 s99, s99, 15
	s_add_u32 s100, s100, s99
	s_addc_u32 s101, s101, 0
	v_lshlrev_b32_e32 v250, 4, v202
	global_store_dwordx4 v250, v[132:135], s[100:101] sc0 sc1
	global_store_dwordx4 v250, v[128:131], s[100:101] offset:1024 sc0 sc1
	global_store_dwordx4 v250, v[116:119], s[100:101] offset:2048 sc0 sc1
	global_store_dwordx4 v250, v[106:109], s[100:101] offset:3072 sc0 sc1
	s_add_u32 s100, s100, 0x1000
	s_addc_u32 s101, s101, 0
	global_store_dwordx4 v250, v[94:97], s[100:101] sc0 sc1
	global_store_dwordx4 v250, v[90:93], s[100:101] offset:1024 sc0 sc1
	global_store_dwordx4 v250, v[78:81], s[100:101] offset:2048 sc0 sc1
	global_store_dwordx4 v250, v[74:77], s[100:101] offset:3072 sc0 sc1
	s_add_u32 s100, s100, 0x1000
	s_addc_u32 s101, s101, 0
	global_store_dwordx4 v250, v[124:127], s[100:101] sc0 sc1
	global_store_dwordx4 v250, v[120:123], s[100:101] offset:1024 sc0 sc1
	global_store_dwordx4 v250, v[102:105], s[100:101] offset:2048 sc0 sc1
	global_store_dwordx4 v250, v[98:101], s[100:101] offset:3072 sc0 sc1
	s_add_u32 s100, s100, 0x1000
	s_addc_u32 s101, s101, 0
	global_store_dwordx4 v250, v[86:89], s[100:101] sc0 sc1
	global_store_dwordx4 v250, v[82:85], s[100:101] offset:1024 sc0 sc1
	global_store_dwordx4 v250, v[70:73], s[100:101] offset:2048 sc0 sc1
	global_store_dwordx4 v250, v[66:69], s[100:101] offset:3072 sc0 sc1
	s_add_u32 s100, s100, 0x1000
	s_addc_u32 s101, s101, 0
	global_store_dwordx4 v250, v[62:65], s[100:101] sc0 sc1
	global_store_dwordx4 v250, v[58:61], s[100:101] offset:1024 sc0 sc1
	global_store_dwordx4 v250, v[46:49], s[100:101] offset:2048 sc0 sc1
	global_store_dwordx4 v250, v[42:45], s[100:101] offset:3072 sc0 sc1
	s_add_u32 s100, s100, 0x1000
	s_addc_u32 s101, s101, 0
	global_store_dwordx4 v250, v[30:33], s[100:101] sc0 sc1
	global_store_dwordx4 v250, v[26:29], s[100:101] offset:1024 sc0 sc1
	global_store_dwordx4 v250, v[14:17], s[100:101] offset:2048 sc0 sc1
	global_store_dwordx4 v250, v[10:13], s[100:101] offset:3072 sc0 sc1
	s_add_u32 s100, s100, 0x1000
	s_addc_u32 s101, s101, 0
	global_store_dwordx4 v250, v[54:57], s[100:101] sc0 sc1
	global_store_dwordx4 v250, v[50:53], s[100:101] offset:1024 sc0 sc1
	global_store_dwordx4 v250, v[38:41], s[100:101] offset:2048 sc0 sc1
	global_store_dwordx4 v250, v[34:37], s[100:101] offset:3072 sc0 sc1
	s_add_u32 s100, s100, 0x1000
	s_addc_u32 s101, s101, 0
	global_store_dwordx4 v250, v[22:25], s[100:101] sc0 sc1
	global_store_dwordx4 v250, v[18:21], s[100:101] offset:1024 sc0 sc1
	global_store_dwordx4 v250, v[6:9], s[100:101] offset:2048 sc0 sc1
	global_store_dwordx4 v250, v[2:5], s[100:101] offset:3072 sc0 sc1
	s_waitcnt vmcnt(0)
	s_barrier
	v_cmp_eq_u32_e32 vcc, 0, v164
	s_and_saveexec_b64 s[100:101], vcc
	s_cbranch_execz .Lmy_sk_pflag
	s_lshr_b32 s99, s2, 1
	s_lshl_b32 s99, s99, 2
	v_mov_b32_e32 v250, s99
	v_mov_b32_e32 v251, 1
	global_atomic_add v250, v251, s[76:77] offset:64 sc1
.Lmy_sk_pflag:
	s_or_b64 exec, exec, s[100:101]
	s_mov_b64 s[8:9], -1
	s_branch .LBB0_704
.Lmy_sk_cons:
	v_cmp_eq_u32_e32 vcc, 0, v164
	s_and_saveexec_b64 s[100:101], vcc
	s_cbranch_execz .Lmy_sk_cgot2
	s_lshr_b32 s99, s2, 1
	s_lshl_b32 s99, s99, 2
	v_mov_b32_e32 v250, s99
	s_mov_b32 s99, 0
.Lmy_sk_spin:
	global_load_dword v251, v250, s[76:77] offset:64 sc1
	s_waitcnt vmcnt(0)
	v_readfirstlane_b32 vcc_lo, v251
	s_cmp_lg_u32 vcc_lo, 0
	s_cbranch_scc1 .Lmy_sk_cgot
	s_sleep 1
	s_add_i32 s99, s99, 1
	s_cmpk_lt_u32 s99, 0x4000
	s_cbranch_scc1 .Lmy_sk_spin
.Lmy_sk_cgot:
	global_store_dword v250, v0, s[76:77] offset:64 sc1
.Lmy_sk_cgot2:
	s_or_b64 exec, exec, s[100:101]
	s_waitcnt vmcnt(0)
	s_barrier
	buffer_inv sc1
	s_lshr_b32 s100, s2, 1
	s_lshl_b32 s100, s100, 18
	s_add_u32 s100, s76, s100
	s_addc_u32 s101, s77, 0
	s_add_u32 s100, s100, 0x1a900000
	s_addc_u32 s101, s101, 0
	v_readfirstlane_b32 s99, v164
	s_lshr_b32 s99, s99, 6
	s_lshl_b32 s99, s99, 15
	s_add_u32 s100, s100, s99
	s_addc_u32 s101, s101, 0
	v_lshlrev_b32_e32 v250, 4, v202
	global_load_dwordx4 v[214:217], v250, s[100:101] sc0 sc1
	global_load_dwordx4 v[218:221], v250, s[100:101] offset:1024 sc0 sc1
	global_load_dwordx4 v[222:225], v250, s[100:101] offset:2048 sc0 sc1
	global_load_dwordx4 v[226:229], v250, s[100:101] offset:3072 sc0 sc1
	s_add_u32 s100, s100, 0x1000
	s_addc_u32 s101, s101, 0
	global_load_dwordx4 v[230:233], v250, s[100:101] sc0 sc1
	global_load_dwordx4 v[234:237], v250, s[100:101] offset:1024 sc0 sc1
	global_load_dwordx4 v[238:241], v250, s[100:101] offset:2048 sc0 sc1
	global_load_dwordx4 v[242:245], v250, s[100:101] offset:3072 sc0 sc1
	s_add_u32 s100, s100, 0x1000
	s_addc_u32 s101, s101, 0
	s_waitcnt vmcnt(7)
	v_pk_add_f32 v[132:133], v[132:133], v[214:215]
	v_pk_add_f32 v[134:135], v[134:135], v[216:217]
	s_waitcnt vmcnt(6)
	v_pk_add_f32 v[128:129], v[128:129], v[218:219]
	v_pk_add_f32 v[130:131], v[130:131], v[220:221]
	s_waitcnt vmcnt(5)
	v_pk_add_f32 v[116:117], v[116:117], v[222:223]
	v_pk_add_f32 v[118:119], v[118:119], v[224:225]
	s_waitcnt vmcnt(4)
	v_pk_add_f32 v[106:107], v[106:107], v[226:227]
	v_pk_add_f32 v[108:109], v[108:109], v[228:229]
	s_waitcnt vmcnt(3)
	v_pk_add_f32 v[94:95], v[94:95], v[230:231]
	v_pk_add_f32 v[96:97], v[96:97], v[232:233]
	s_waitcnt vmcnt(2)
	v_pk_add_f32 v[90:91], v[90:91], v[234:235]
	v_pk_add_f32 v[92:93], v[92:93], v[236:237]
	s_waitcnt vmcnt(1)
	v_pk_add_f32 v[78:79], v[78:79], v[238:239]
	v_pk_add_f32 v[80:81], v[80:81], v[240:241]
	s_waitcnt vmcnt(0)
	v_pk_add_f32 v[74:75], v[74:75], v[242:243]
	v_pk_add_f32 v[76:77], v[76:77], v[244:245]
	global_load_dwordx4 v[214:217], v250, s[100:101] sc0 sc1
	global_load_dwordx4 v[218:221], v250, s[100:101] offset:1024 sc0 sc1
	global_load_dwordx4 v[222:225], v250, s[100:101] offset:2048 sc0 sc1
	global_load_dwordx4 v[226:229], v250, s[100:101] offset:3072 sc0 sc1
	s_add_u32 s100, s100, 0x1000
	s_addc_u32 s101, s101, 0
	global_load_dwordx4 v[230:233], v250, s[100:101] sc0 sc1
	global_load_dwordx4 v[234:237], v250, s[100:101] offset:1024 sc0 sc1
	global_load_dwordx4 v[238:241], v250, s[100:101] offset:2048 sc0 sc1
	global_load_dwordx4 v[242:245], v250, s[100:101] offset:3072 sc0 sc1
	s_add_u32 s100, s100, 0x1000
	s_addc_u32 s101, s101, 0
	s_waitcnt vmcnt(7)
	v_pk_add_f32 v[124:125], v[124:125], v[214:215]
	v_pk_add_f32 v[126:127], v[126:127], v[216:217]
	s_waitcnt vmcnt(6)
	v_pk_add_f32 v[120:121], v[120:121], v[218:219]
	v_pk_add_f32 v[122:123], v[122:123], v[220:221]
	s_waitcnt vmcnt(5)
	v_pk_add_f32 v[102:103], v[102:103], v[222:223]
	v_pk_add_f32 v[104:105], v[104:105], v[224:225]
	s_waitcnt vmcnt(4)
	v_pk_add_f32 v[98:99], v[98:99], v[226:227]
	v_pk_add_f32 v[100:101], v[100:101], v[228:229]
	s_waitcnt vmcnt(3)
	v_pk_add_f32 v[86:87], v[86:87], v[230:231]
	v_pk_add_f32 v[88:89], v[88:89], v[232:233]
	s_waitcnt vmcnt(2)
	v_pk_add_f32 v[82:83], v[82:83], v[234:235]
	v_pk_add_f32 v[84:85], v[84:85], v[236:237]
	s_waitcnt vmcnt(1)
	v_pk_add_f32 v[70:71], v[70:71], v[238:239]
	v_pk_add_f32 v[72:73], v[72:73], v[240:241]
	s_waitcnt vmcnt(0)
	v_pk_add_f32 v[66:67], v[66:67], v[242:243]
	v_pk_add_f32 v[68:69], v[68:69], v[244:245]
	global_load_dwordx4 v[214:217], v250, s[100:101] sc0 sc1
	global_load_dwordx4 v[218:221], v250, s[100:101] offset:1024 sc0 sc1
	global_load_dwordx4 v[222:225], v250, s[100:101] offset:2048 sc0 sc1
	global_load_dwordx4 v[226:229], v250, s[100:101] offset:3072 sc0 sc1
	s_add_u32 s100, s100, 0x1000
	s_addc_u32 s101, s101, 0
	global_load_dwordx4 v[230:233], v250, s[100:101] sc0 sc1
	global_load_dwordx4 v[234:237], v250, s[100:101] offset:1024 sc0 sc1
	global_load_dwordx4 v[238:241], v250, s[100:101] offset:2048 sc0 sc1
	global_load_dwordx4 v[242:245], v250, s[100:101] offset:3072 sc0 sc1
	s_add_u32 s100, s100, 0x1000
	s_addc_u32 s101, s101, 0
	s_waitcnt vmcnt(7)
	v_pk_add_f32 v[62:63], v[62:63], v[214:215]
	v_pk_add_f32 v[64:65], v[64:65], v[216:217]
	s_waitcnt vmcnt(6)
	v_pk_add_f32 v[58:59], v[58:59], v[218:219]
	v_pk_add_f32 v[60:61], v[60:61], v[220:221]
	s_waitcnt vmcnt(5)
	v_pk_add_f32 v[46:47], v[46:47], v[222:223]
	v_pk_add_f32 v[48:49], v[48:49], v[224:225]
	s_waitcnt vmcnt(4)
	v_pk_add_f32 v[42:43], v[42:43], v[226:227]
	v_pk_add_f32 v[44:45], v[44:45], v[228:229]
	s_waitcnt vmcnt(3)
	v_pk_add_f32 v[30:31], v[30:31], v[230:231]
	v_pk_add_f32 v[32:33], v[32:33], v[232:233]
	s_waitcnt vmcnt(2)
	v_pk_add_f32 v[26:27], v[26:27], v[234:235]
	v_pk_add_f32 v[28:29], v[28:29], v[236:237]
	s_waitcnt vmcnt(1)
	v_pk_add_f32 v[14:15], v[14:15], v[238:239]
	v_pk_add_f32 v[16:17], v[16:17], v[240:241]
	s_waitcnt vmcnt(0)
	v_pk_add_f32 v[10:11], v[10:11], v[242:243]
	v_pk_add_f32 v[12:13], v[12:13], v[244:245]
	global_load_dwordx4 v[214:217], v250, s[100:101] sc0 sc1
	global_load_dwordx4 v[218:221], v250, s[100:101] offset:1024 sc0 sc1
	global_load_dwordx4 v[222:225], v250, s[100:101] offset:2048 sc0 sc1
	global_load_dwordx4 v[226:229], v250, s[100:101] offset:3072 sc0 sc1
	s_add_u32 s100, s100, 0x1000
	s_addc_u32 s101, s101, 0
	global_load_dwordx4 v[230:233], v250, s[100:101] sc0 sc1
	global_load_dwordx4 v[234:237], v250, s[100:101] offset:1024 sc0 sc1
	global_load_dwordx4 v[238:241], v250, s[100:101] offset:2048 sc0 sc1
	global_load_dwordx4 v[242:245], v250, s[100:101] offset:3072 sc0 sc1
	s_waitcnt vmcnt(7)
	v_pk_add_f32 v[54:55], v[54:55], v[214:215]
	v_pk_add_f32 v[56:57], v[56:57], v[216:217]
	s_waitcnt vmcnt(6)
	v_pk_add_f32 v[50:51], v[50:51], v[218:219]
	v_pk_add_f32 v[52:53], v[52:53], v[220:221]
	s_waitcnt vmcnt(5)
	v_pk_add_f32 v[38:39], v[38:39], v[222:223]
	v_pk_add_f32 v[40:41], v[40:41], v[224:225]
	s_waitcnt vmcnt(4)
	v_pk_add_f32 v[34:35], v[34:35], v[226:227]
	v_pk_add_f32 v[36:37], v[36:37], v[228:229]
	s_waitcnt vmcnt(3)
	v_pk_add_f32 v[22:23], v[22:23], v[230:231]
	v_pk_add_f32 v[24:25], v[24:25], v[232:233]
	s_waitcnt vmcnt(2)
	v_pk_add_f32 v[18:19], v[18:19], v[234:235]
	v_pk_add_f32 v[20:21], v[20:21], v[236:237]
	s_waitcnt vmcnt(1)
	v_pk_add_f32 v[6:7], v[6:7], v[238:239]
	v_pk_add_f32 v[8:9], v[8:9], v[240:241]
	s_waitcnt vmcnt(0)
	v_pk_add_f32 v[2:3], v[2:3], v[242:243]
	v_pk_add_f32 v[4:5], v[4:5], v[244:245]
	s_branch .Lmy_sk_norm
